# layer-0 w_down conversion moved from phase 0b into phase A(0) on WGs 128-255 (same balance trick as other layers)
# baseline (speedup 1.0000x reference)
.LBB0_40:
	s_add_i32 s60, s60, s30
	s_add_i32 s15, s15, s16
	s_add_i32 s59, s59, s17
	s_add_i32 s18, s18, s19
	s_cmpk_lt_i32 s60, 0x730
	s_cbranch_scc0 .LBB0_142

.Lmy_cvt0:
	v_readlane_b32 s0, v252, 47
	v_readlane_b32 s1, v252, 48
	s_andn2_b64 vcc, exec, s[0:1]
	s_cbranch_vccnz .LBB0_368
	s_cmp_lt_u32 s2, 0x80
	s_cbranch_scc1 .LBB0_368
	s_bfe_i64 s[0:1], s[52:53], 0x200000
	v_readlane_b32 s72, v252, 61
	s_lshl_b64 s[0:1], s[0:1], 13
	v_readlane_b32 s82, v253, 7
	v_readlane_b32 s83, v253, 8
	s_add_u32 s0, s82, s0
	s_addc_u32 s1, s83, s1
	s_mov_b64 s[6:7], s[38:39]
	v_readlane_b32 s36, v254, 50
	s_add_u32 s4, s0, 0xffffe000
	v_readlane_b32 s44, v254, 58
	v_readlane_b32 s80, v253, 5
	s_addc_u32 s5, s1, -1
	s_lshl_b64 s[0:1], s[52:53], 26
	s_lshl_b64 s[12:13], s[52:53], 13
	s_lshl_b64 s[18:19], s[52:53], 24
	s_lshl_b32 s16, s52, 4
	s_lshl_b64 s[20:21], s[52:53], 22
	v_readlane_b32 s38, v254, 52
	v_readlane_b32 s39, v254, 53
	s_lshl_b32 s44, s52, 9
	v_readlane_b32 s81, v253, 6
	s_mov_b64 s[38:39], s[6:7]
	s_add_u32 s6, s80, s0
	v_readlane_b32 s78, v253, 3
	s_addc_u32 s7, s81, s1
	v_readlane_b32 s79, v253, 4
	s_add_u32 s8, s78, s0
	v_readlane_b32 s74, v252, 63
	v_readlane_b32 s40, v254, 54
	s_addc_u32 s9, s79, s1
	v_readlane_b32 s75, v253, 0
	v_readlane_b32 s37, v254, 51
	v_readlane_b32 s41, v254, 55
	s_add_u32 s40, s74, s12
	v_readlane_b32 s42, v254, 56
	s_addc_u32 s41, s75, s13
	s_mov_b32 s1, s37
	v_readlane_b32 s73, v252, 62
	v_readlane_b32 s76, v253, 1
	v_readlane_b32 s77, v253, 2
	v_readlane_b32 s43, v254, 57
	v_readlane_b32 s45, v254, 59
	v_readlane_b32 s46, v254, 60
	v_readlane_b32 s47, v254, 61
	v_readlane_b32 s48, v254, 62
	v_readlane_b32 s49, v254, 63
	s_add_u32 s42, s72, s18
	v_writelane_b32 v254, s0, 50
	s_addc_u32 s43, s73, s19
	v_readlane_b32 s68, v252, 6
	v_writelane_b32 v254, s1, 51
	v_readlane_b32 s84, v253, 9
	v_readlane_b32 s85, v253, 10
	v_readlane_b32 s86, v253, 11
	v_readlane_b32 s87, v253, 12
	v_readlane_b32 s72, v252, 10
	v_readlane_b32 s73, v252, 11
	v_readlane_b32 s74, v252, 12
	v_readlane_b32 s75, v252, 13
	v_readlane_b32 s76, v252, 14
	v_readlane_b32 s77, v252, 15
	v_readlane_b32 s78, v252, 16
	v_readlane_b32 s79, v252, 17
	v_readlane_b32 s80, v252, 18
	v_readlane_b32 s81, v252, 19
	v_readlane_b32 s82, v252, 20
	v_readlane_b32 s83, v252, 21
	v_writelane_b32 v254, s2, 52
	v_writelane_b32 v254, s3, 53
	v_readlane_b32 s72, v252, 22
	v_writelane_b32 v254, s4, 54
	v_readlane_b32 s73, v252, 23
	v_readlane_b32 s74, v252, 24
	v_readlane_b32 s75, v252, 25
	v_readlane_b32 s76, v252, 26
	v_readlane_b32 s77, v252, 27
	v_readlane_b32 s78, v252, 28
	v_readlane_b32 s79, v252, 29
	v_readlane_b32 s80, v252, 30
	v_readlane_b32 s81, v252, 31
	v_readlane_b32 s82, v252, 32
	v_readlane_b32 s83, v252, 33
	v_readlane_b32 s50, v255, 0
	v_readlane_b32 s51, v255, 1
	s_mov_b32 s45, s37
	v_readlane_b32 s69, v252, 7
	s_add_u32 s46, s68, s20
	v_writelane_b32 v254, s5, 55
	v_writelane_b32 v255, s14, 0
	v_readlane_b32 s84, v252, 34
	v_readlane_b32 s85, v252, 35
	v_readlane_b32 s86, v252, 36
	v_readlane_b32 s87, v252, 37
	s_mov_b64 s[72:73], s[76:77]
	s_addc_u32 s47, s69, s21
	v_writelane_b32 v254, s6, 56
	v_writelane_b32 v255, s15, 1
	s_lshl_b64 s[0:1], s[44:45], 2
	s_mov_b64 s[74:75], s[78:79]
	s_mov_b64 s[76:77], s[80:81]
	s_mov_b64 s[78:79], s[82:83]
	s_mov_b64 s[80:81], s[84:85]
	v_writelane_b32 v254, s7, 57
	s_add_u32 s48, s80, s0
	s_mul_i32 s22, s52, 0x300000
	v_writelane_b32 v254, s8, 58
	s_mov_b64 s[82:83], s[86:87]
	s_addc_u32 s49, s81, s1
	s_mul_hi_u32 s17, s52, 0x300000
	v_writelane_b32 v254, s9, 59
	s_add_u32 s50, s82, s22
	v_writelane_b32 v254, s10, 60
	s_addc_u32 s51, s83, s17
	v_writelane_b32 v254, s11, 61
	s_add_u32 s58, s78, s0
	v_readlane_b32 s70, v252, 8
	v_writelane_b32 v254, s12, 62
	s_addc_u32 s59, s79, s1
	s_mul_i32 s1, s52, 0x1880000
	v_readlane_b32 s71, v252, 9
	v_writelane_b32 v254, s13, 63
	s_mul_hi_u32 s0, s52, 0x1880000
	s_add_u32 s70, s76, s1
	s_addc_u32 s71, s77, s0
	s_movk_i32 s17, 0x4000
	s_movk_i32 s18, 0x100
	v_readlane_b32 s19, v254, 38
	v_readlane_b32 s20, v254, 36
	v_readlane_b32 s21, v254, 32
	v_readlane_b32 s22, v252, 46
	s_nop 3
	s_addk_i32 s19, 0xff00
	s_addk_i32 s20, 0xfc00
	s_addk_i32 s21, 0xc000
	s_addk_i32 s22, 0xff80
	s_branch .LBB0_269
